# code warm-up loads limited to the code size; otherwise as the previous version (four-workgroup barrier 6, split barriers 4 and 5)
# speedup vs baseline: 1.0195x; 1.0043x over previous
; #define LAS __attribute__((address_space(3)))
; DI void p0_prep(const Params& p, LAS unsigned char* lds) {
;     int tid = threadIdx.x; asm volatile("" : "+v"(tid));
;     const int lane = tid & 63, wid = __builtin_amdgcn_readfirstlane(tid >> 6);
;     const int gw = blockIdx.x * 8 + wid, NGW = gridDim.x * 8;
;     unsigned char* ws = p.ws;
;     LAS float* scr = (LAS float*)(lds + wid * 8448);
;     constexpr int J1 = 28 * 128, J2 = J1 + 256, J3 = J2 + 256, J4 = J3 + 256, J5 = J4 + 128, J6 = J5 + 512;
;     for (int it = gw; it < J6; it += NGW) {
;         if (it < J1) {
;             int t = it >> 7; const int rem = it & 127, g = rem >> 4, kb = rem & 15; if (t >= 12) t += 1;
;             const bool sw = (t == 4 || t == 5 || t == 10 || t == 11);
;             const int src = (t < 12 ? 256 * t : 256 * (t - 1) + 16) + 32 * (sw ? g : lgrp(g));
;             transpose_item(p.w_in + (size_t)(64 * kb) * 7184 + src, 7184, (bf16_t*)(ws + OFF_WINT) + (size_t)(t * 256 + 32 * g) * 1024 + 64 * kb, 1024, scr, lane);
.LBB0_18:
	s_or_b64 exec, exec, s[4:5]
	s_getpc_b64 s[100:101]
	s_lshr_b32 s4, s2, 3
	s_lshl_b32 s4, s4, 13
	v_lshlrev_b32_e32 v168, 4, v203
	v_add_u32_e32 v168, s4, v168
	v_cmp_gt_u32_e32 vcc, 0x26c00, v168
	s_and_saveexec_b64 s[4:5], vcc
	global_load_dwordx4 v[172:175], v168, s[100:101]
	s_or_b64 exec, exec, s[4:5]
	v_mov_b32_e32 v87, v203
	s_lshl_b32 s49, s2, 3
	v_readfirstlane_b32 s3, v87
	s_ashr_i32 s8, s3, 6
	s_load_dword s3, s[0:1], 0xd0
	s_add_i32 s20, s8, s49
	s_add_u32 s4, s0, 0xd0
	s_addc_u32 s5, s1, 0
	v_and_b32_e32 v1, 63, v87
	v_writelane_b32 v255, s4, 2
	s_waitcnt lgkmcnt(0)
	s_lshl_b32 s74, s3, 3
	s_cmpk_gt_i32 s20, 0x137f
	v_writelane_b32 v255, s5, 3
	v_lshlrev_b32_e32 v66, 3, v1
	s_cbranch_scc1 .LBB0_37
	s_mul_i32 s4, s8, 0x2100
	v_lshrrev_b32_e32 v75, 3, v1
	v_and_b32_e32 v0, 56, v66
	s_add_i32 s4, s4, 0
	v_lshrrev_b32_e32 v70, 5, v1
	v_and_b32_e32 v68, 31, v87
	v_mul_u32_u24_e32 v2, 0x84, v0
	v_lshlrev_b32_e32 v3, 2, v75
	v_or_b32_e32 v48, 24, v70
	v_add3_u32 v3, s4, v2, v3
	v_lshl_or_b32 v2, v70, 9, v68
	v_or_b32_e32 v60, 36, v70
	v_lshlrev_b32_e32 v5, 2, v2
	v_lshl_or_b32 v2, v48, 9, v68
	v_or_b32_e32 v72, 42, v70
	v_lshlrev_b32_e32 v29, 2, v2
	v_lshl_or_b32 v2, v60, 9, v68
	v_or_b32_e32 v74, 46, v70
	v_lshlrev_b32_e32 v41, 2, v2
	v_lshl_or_b32 v2, v72, 9, v68
	v_lshlrev_b32_e32 v47, 2, v2
	v_lshl_or_b32 v2, v74, 9, v68
	v_or_b32_e32 v76, 48, v70
	v_lshlrev_b32_e32 v51, 2, v2
	v_lshl_or_b32 v2, v76, 9, v68
	v_or_b32_e32 v77, 50, v70
	v_lshlrev_b32_e32 v53, 2, v2
	v_lshl_or_b32 v2, v77, 9, v68
	v_or_b32_e32 v78, 52, v70
	v_lshlrev_b32_e32 v55, 2, v2
	v_lshl_or_b32 v2, v78, 9, v68
	v_or_b32_e32 v79, 54, v70
	v_lshlrev_b32_e32 v57, 2, v2
	v_lshl_or_b32 v2, v79, 9, v68
	v_or_b32_e32 v80, 56, v70
	v_or_b32_e32 v26, 2, v70
	v_lshlrev_b32_e32 v59, 2, v2
	v_lshl_or_b32 v2, v80, 9, v68
	v_or_b32_e32 v81, 58, v70
	v_or_b32_e32 v50, 26, v70
	v_lshl_or_b32 v4, v26, 9, v68
	v_lshlrev_b32_e32 v61, 2, v2
	v_lshl_or_b32 v2, v81, 9, v68
	v_or_b32_e32 v82, 60, v70
	v_or_b32_e32 v62, 38, v70
	v_lshlrev_b32_e32 v7, 2, v4
	v_lshl_or_b32 v4, v50, 9, v68
	v_lshlrev_b32_e32 v63, 2, v2
	v_lshl_or_b32 v2, v82, 9, v68
	v_or_b32_e32 v83, 62, v70
	v_or_b32_e32 v73, 44, v70
	v_lshlrev_b32_e32 v31, 2, v4
	v_lshl_or_b32 v4, v62, 9, v68
	v_lshlrev_b32_e32 v67, 2, v2
	v_lshl_or_b32 v2, v83, 9, v68
	s_movk_i32 s5, 0x1c10
	v_lshlrev_b32_e32 v43, 2, v4
	v_lshl_or_b32 v4, v73, 9, v68
	v_lshlrev_b32_e32 v69, 2, v2
	v_mad_u32_u24 v2, v70, s5, v68
	v_lshlrev_b32_e32 v49, 2, v4
	v_add_u32_e32 v4, 0x3820, v2
	v_lshlrev_b32_e32 v89, 2, v4
	v_add_u32_e32 v4, 0x7040, v2
	v_lshlrev_b32_e32 v91, 2, v4
	v_add_u32_e32 v4, 0xa860, v2
	v_lshlrev_b32_e32 v93, 2, v4
	v_add_u32_e32 v4, 0xe080, v2
	v_lshlrev_b32_e32 v102, 2, v4
	v_add_u32_e32 v4, 0x118a0, v2
	v_lshlrev_b32_e32 v103, 2, v4
	v_add_u32_e32 v4, 0x150c0, v2
	v_lshlrev_b32_e32 v104, 2, v4
	v_add_u32_e32 v4, 0x188e0, v2
	v_lshlrev_b32_e32 v105, 2, v4
	v_add_u32_e32 v4, 0x1c100, v2
	v_lshlrev_b32_e32 v106, 2, v4
	v_add_u32_e32 v4, 0x1f920, v2
	v_lshlrev_b32_e32 v107, 2, v4
	v_add_u32_e32 v4, 0x23140, v2
	v_lshlrev_b32_e32 v108, 2, v4
	v_add_u32_e32 v4, 0x26960, v2
	v_lshlrev_b32_e32 v109, 2, v4
	v_add_u32_e32 v4, 0x2a180, v2
	v_lshlrev_b32_e32 v110, 2, v4
	v_add_u32_e32 v4, 0x2d9a0, v2
	v_lshlrev_b32_e32 v111, 2, v4
	v_add_u32_e32 v4, 0x311c0, v2
	v_lshlrev_b32_e32 v112, 2, v4
	v_add_u32_e32 v4, 0x349e0, v2
	v_lshlrev_b32_e32 v113, 2, v4
	v_add_u32_e32 v4, 0x38200, v2
	v_lshlrev_b32_e32 v114, 2, v4
	v_add_u32_e32 v4, 0x3ba20, v2
	v_lshlrev_b32_e32 v115, 2, v4
	v_add_u32_e32 v4, 0x3f240, v2
	v_lshlrev_b32_e32 v116, 2, v4
	v_add_u32_e32 v4, 0x42a60, v2
	v_lshlrev_b32_e32 v117, 2, v4
	v_add_u32_e32 v4, 0x46280, v2
	v_lshlrev_b32_e32 v118, 2, v4
	v_add_u32_e32 v4, 0x49aa0, v2
	v_lshlrev_b32_e32 v119, 2, v4
	v_add_u32_e32 v4, 0x4d2c0, v2
	v_lshlrev_b32_e32 v120, 2, v4
	v_add_u32_e32 v4, 0x50ae0, v2
	v_lshlrev_b32_e32 v121, 2, v4
	v_add_u32_e32 v4, 0x54300, v2
	v_lshlrev_b32_e32 v122, 2, v4
	v_add_u32_e32 v4, 0x57b20, v2
	v_lshlrev_b32_e32 v123, 2, v4
	v_add_u32_e32 v4, 0x5b340, v2
	v_lshlrev_b32_e32 v124, 2, v4
	v_add_u32_e32 v4, 0x5eb60, v2
	v_lshlrev_b32_e32 v125, 2, v4
	v_add_u32_e32 v4, 0x62380, v2
	v_lshlrev_b32_e32 v126, 2, v4
	v_add_u32_e32 v4, 0x65ba0, v2
	v_lshlrev_b32_e32 v127, 2, v4
	v_add_u32_e32 v4, 0x693c0, v2
	v_lshlrev_b32_e32 v129, 2, v2
; DI void transpose_item(const float* W, int ldw, bf16_t* WT, int ldt, LAS float* scr, int lane) {
;     float tv[32];
; #pragma unroll
;     for (int i = 0; i < 32; ++i) tv[i] = W[(size_t)(2 * i + (lane >> 5)) * ldw + (lane & 31)];
; #pragma unroll
;     for (int i = 0; i < 32; ++i) scr[(2 * i + (lane >> 5)) * 33 + (lane & 31)] = tv[i];
;     LDS_WAIT();
;     const int c = lane & 7;
; #pragma unroll
;     for (int j = 0; j < 4; ++j) {
;         const int n = (lane >> 3) + 8 * j; const LAS float* s = scr + (8 * c) * 33 + n;
;         u32x4 o; o.x = pk2(s[0 * 33], s[1 * 33]); o.y = pk2(s[2 * 33], s[3 * 33]); o.z = pk2(s[4 * 33], s[5 * 33]); o.w = pk2(s[6 * 33], s[7 * 33]);
;         *(u32x4*)(WT + (size_t)n * ldt + 8 * c) = o;
; DI void p0_prep(const Params& p, LAS unsigned char* lds) {
;     ...
;     for (int it = gw; it < J6; it += NGW) {
;         if (it < J1) {
;             int t = it >> 7; const int rem = it & 127, g = rem >> 4, kb = rem & 15; if (t >= 12) t += 1;
;             const bool sw = (t == 4 || t == 5 || t == 10 || t == 11);
;             const int src = (t < 12 ? 256 * t : 256 * (t - 1) + 16) + 32 * (sw ? g : lgrp(g));
;             transpose_item(p.w_in + (size_t)(64 * kb) * 7184 + src, 7184, (bf16_t*)(ws + OFF_WINT) + (size_t)(t * 256 + 32 * g) * 1024 + 64 * kb, 1024, scr, lane);
;         } else if (it < J2) {
;             const int j = it - J1, t = j >> 7, rem = j & 127, g = rem >> 4, kb = rem & 15;
;             const int src = 256 * t + 32 * (t ? g : lgrp(g));
;             transpose_item(p.w_mem_kv + (size_t)(64 * kb) * 512 + src, 512, (bf16_t*)(ws + OFF_WMEM) + (size_t)(t * 256 + 32 * g) * 1024 + 64 * kb, 1024, scr, lane);
;         } else if (it < J4) {
;             const int j0 = it - J2, which = j0 >> 8, j = j0 & 255, t = j >> 6, rem = j & 63, g = rem >> 3, kb = rem & 7;
;             const float* W = which ? p.w_up_b : p.w_up_a;
;             transpose_item(W + (size_t)(64 * kb) * 1024 + 256 * t + 32 * lgrp(g), 1024, (bf16_t*)(ws + (which ? OFF_WUPB : OFF_WUPA)) + (size_t)(t * 256 + 32 * g) * 512 + 64 * kb, 512, scr, lane);
;         } else if (it < J5) {
;             const int j = it - J4, t = j >> 5, rem = j & 31, g = rem >> 2, kb = rem & 3;
;             transpose_item(p.w_up_m + (size_t)(64 * kb) * 1024 + 256 * t + 32 * lgrp(g), 1024, (bf16_t*)(ws + OFF_WUPM) + (size_t)(t * 256 + 32 * g) * 256 + 64 * kb, 256, scr, lane);
	v_add_u32_e32 v2, 0x6cbe0, v2
	v_lshlrev_b32_e32 v130, 2, v2
	s_movk_i32 s5, 0x84
	v_mov_b32_e32 v2, 0x630
	v_mad_u32_u24 v131, v70, s5, v2
	v_mov_b32_e32 v2, 0xc60
	v_mad_u32_u24 v132, v70, s5, v2
	v_mov_b32_e32 v2, 0x1290
	v_mad_u32_u24 v133, v70, s5, v2
	v_mov_b32_e32 v2, 0x18c0
	v_or_b32_e32 v28, 4, v70
	v_mad_u32_u24 v134, v70, s5, v2
	v_lshl_add_u32 v135, v68, 2, s4
	s_load_dwordx4 s[4:7], s[0:1], 0xb0
	s_load_dwordx2 s[10:11], s[0:1], 0x88
	s_load_dwordx2 s[12:13], s[0:1], 0x48
	v_or_b32_e32 v30, 6, v70
	v_or_b32_e32 v32, 8, v70
	v_or_b32_e32 v34, 10, v70
	v_or_b32_e32 v38, 14, v70
	v_or_b32_e32 v42, 18, v70
	v_or_b32_e32 v52, 28, v70
	v_lshl_or_b32 v6, v28, 9, v68
	v_or_b32_e32 v36, 12, v70
	v_or_b32_e32 v40, 16, v70
	v_or_b32_e32 v44, 20, v70
	v_or_b32_e32 v46, 22, v70
	v_or_b32_e32 v54, 30, v70
	v_or_b32_e32 v56, 32, v70
	v_or_b32_e32 v58, 34, v70
	v_or_b32_e32 v71, 40, v70
	v_lshl_or_b32 v8, v30, 9, v68
	v_lshl_or_b32 v10, v32, 9, v68
	v_lshl_or_b32 v12, v34, 9, v68
	v_lshl_or_b32 v16, v38, 9, v68
	v_lshl_or_b32 v20, v42, 9, v68
	v_lshlrev_b32_e32 v9, 2, v6
	v_lshl_or_b32 v6, v52, 9, v68
	v_lshl_or_b32 v14, v36, 9, v68
	v_lshl_or_b32 v18, v40, 9, v68
	v_lshl_or_b32 v22, v44, 9, v68
	v_lshl_or_b32 v24, v46, 9, v68
	v_lshlrev_b32_e32 v11, 2, v8
	v_lshlrev_b32_e32 v13, 2, v10
	v_lshlrev_b32_e32 v15, 2, v12
	v_lshl_or_b32 v8, v54, 9, v68
	v_lshlrev_b32_e32 v19, 2, v16
	v_lshl_or_b32 v10, v56, 9, v68
	v_lshlrev_b32_e32 v23, 2, v20
	v_lshl_or_b32 v12, v58, 9, v68
	v_lshlrev_b32_e32 v33, 2, v6
	v_lshl_or_b32 v6, v71, 9, v68
	v_lshl_or_b32 v2, v26, 10, v68
	v_lshl_or_b32 v16, v40, 10, v68
	v_lshl_or_b32 v20, v44, 10, v68
	v_lshl_or_b32 v26, v50, 10, v68
	v_lshl_or_b32 v40, v71, 10, v68
	v_lshl_or_b32 v44, v73, 10, v68
	v_lshl_or_b32 v50, v77, 10, v68
	v_or_b32_e32 v71, 8, v75
	v_or_b32_e32 v73, 16, v75
	v_or_b32_e32 v77, 24, v75
	v_lshlrev_b32_e32 v17, 2, v14
	v_lshlrev_b32_e32 v21, 2, v18
	v_lshlrev_b32_e32 v25, 2, v22
	v_lshlrev_b32_e32 v27, 2, v24
	v_lshlrev_b32_e32 v35, 2, v8
	v_lshlrev_b32_e32 v37, 2, v10
	v_lshlrev_b32_e32 v39, 2, v12
	v_lshlrev_b32_e32 v45, 2, v6
	v_lshlrev_b32_e32 v128, 2, v4
	s_mov_b64 s[14:15], 0x1100000
	v_lshl_or_b32 v4, v28, 10, v68
	v_lshl_or_b32 v6, v30, 10, v68
	v_lshl_or_b32 v8, v32, 10, v68
	v_lshl_or_b32 v10, v34, 10, v68
	v_lshl_or_b32 v12, v36, 10, v68
	v_lshl_or_b32 v14, v38, 10, v68
	v_lshl_or_b32 v18, v42, 10, v68
	v_lshl_or_b32 v22, v46, 10, v68
	v_lshl_or_b32 v24, v48, 10, v68
	v_lshl_or_b32 v28, v52, 10, v68
	v_lshl_or_b32 v30, v54, 10, v68
	v_lshl_or_b32 v32, v56, 10, v68
	v_lshl_or_b32 v34, v58, 10, v68
	v_lshl_or_b32 v36, v60, 10, v68
	v_lshl_or_b32 v38, v62, 10, v68
	v_lshl_or_b32 v42, v72, 10, v68
	v_lshl_or_b32 v46, v74, 10, v68
	v_lshl_or_b32 v48, v76, 10, v68
	v_lshl_or_b32 v52, v78, 10, v68
	v_lshl_or_b32 v54, v79, 10, v68
	v_lshl_or_b32 v56, v80, 10, v68
	v_lshl_or_b32 v58, v81, 10, v68
	v_lshl_or_b32 v60, v82, 10, v68
	v_lshl_or_b32 v62, v83, 10, v68
	v_lshl_or_b32 v68, v70, 10, v68
	v_mul_u32_u24_e32 v136, 0x84, v70
	s_mov_b64 s[28:29], 0x1080000
	s_mov_b64 s[30:31], 0x1300000
	s_lshl_b32 s16, s2, 4
	s_lshl_b32 s17, s8, 1
	s_lshl_b32 s18, s2, 6
	s_lshl_b32 s19, s8, 3
	s_lshl_b32 s21, s2, 9
	s_lshl_b32 s22, s8, 6
	s_lshl_b32 s23, s2, 5
	s_lshl_b32 s8, s8, 2
	v_lshlrev_b32_e32 v70, 8, v75
	v_lshlrev_b32_e32 v72, 8, v71
	v_lshlrev_b32_e32 v74, 8, v73
	v_lshlrev_b32_e32 v76, 8, v77
	v_lshlrev_b32_e32 v78, 9, v75
	v_lshlrev_b32_e32 v80, 9, v71
	v_lshlrev_b32_e32 v82, 9, v73
	v_lshlrev_b32_e32 v84, 9, v77
	s_mov_b32 s9, 0
	s_add_i32 s16, s16, s17
	s_lshl_b32 s17, s3, 4
	s_add_i32 s18, s18, s19
	s_lshl_b32 s19, s3, 6
	s_add_i32 s21, s21, s22
	s_lshl_b32 s22, s3, 9
	s_add_i32 s23, s23, s8
	s_lshl_b32 s24, s3, 5
	v_lshlrev_b32_e32 v70, 1, v70
	v_lshlrev_b32_e32 v72, 1, v72
	v_lshlrev_b32_e32 v74, 1, v74
	v_lshlrev_b32_e32 v76, 1, v76
	s_mov_b32 s25, 0xe80000
	s_movk_i32 s26, 0xa0
	v_lshlrev_b32_e32 v78, 1, v78
	v_lshlrev_b32_e32 v80, 1, v80
	v_lshlrev_b32_e32 v82, 1, v82
	v_lshlrev_b32_e32 v84, 1, v84
	s_mov_b32 s27, s20
	v_lshlrev_b32_e32 v86, 10, v75
	v_lshlrev_b32_e32 v88, 10, v71
	v_lshlrev_b32_e32 v90, 10, v73
	v_lshlrev_b32_e32 v92, 10, v77
	v_lshl_add_u64 v[94:95], v[64:65], 0, s[14:15]
	v_mov_b32_e32 v97, 0
	v_lshl_add_u64 v[98:99], v[64:65], 0, s[28:29]
	v_lshl_add_u64 v[100:101], v[64:65], 0, s[30:31]
	s_branch .LBB0_21

; DI void xcd_barrier(const XcdBarrier& b) {
;     ...
;             __builtin_amdgcn_fence(__ATOMIC_ACQUIRE, "agent");
;             asm volatile("s_waitcnt vmcnt(0)" ::: "memory");
.Lgb_acq:
	buffer_inv sc1
	s_waitcnt vmcnt(0)
	s_branch .Lgb_join
